# v76: transposing norm chained behind its residual GEMM (block = the workgroup's own tile rows, per-panel counter instead of the grid barrier)
# baseline (speedup 1.0000x reference)
.Ladh_skip:
	v_readlane_b32 s52, v254, 59
	s_and_b64 vcc, exec, s[70:71]
	v_readlane_b32 s53, v254, 60
	s_cbranch_vccz .LBB0_899
	v_mov_b32_e32 v0, v1
	s_cmpk_gt_i32 s67, 0xbf
	s_cbranch_scc1 .LBB0_899
	v_readlane_b32 s16, v255, 5
	s_and_b32 s7, s80, 3
	s_ashr_i32 s0, s80, 2
	v_readlane_b32 s18, v255, 7
	v_readlane_b32 s19, v255, 8
	s_add_u32 s2, s18, 0xd000000
	v_readlane_b32 s13, v254, 63
	s_addc_u32 s3, s19, 0
	v_mbcnt_lo_u32_b32 v0, -1, v0
	s_lshl_b32 s12, s13, 3
	s_mul_i32 s1, s7, 0x3000
	s_load_dwordx2 s[8:9], s[60:61], 0x58
	s_waitcnt vmcnt(0)
	v_mbcnt_hi_u32_b32 v6, -1, v0
	s_mul_i32 s0, s0, 3
	s_add_u32 s1, s58, s1
	v_lshl_add_u32 v4, s13, 6, v6
	s_addc_u32 s6, s59, 0
	s_add_i32 s10, s0, s7
	s_ashr_i32 s11, s10, 31
	v_lshl_add_u32 v35, v4, 2, 0
	v_lshlrev_b32_e32 v7, 1, v4
	v_mov_b64_e32 v[4:5], s[2:3]
	s_movk_i32 s7, 0x6000
	s_lshl_b64 s[10:11], s[10:11], 12
	v_mad_i64_i32 v[22:23], s[2:3], v7, s7, v[4:5]
	v_or_b32_e32 v7, 1, v7
	v_lshlrev_b32_e32 v18, 2, v6
	s_waitcnt lgkmcnt(0)
	s_add_u32 s8, s8, s10
	v_mad_i64_i32 v[24:25], s[2:3], v7, s7, v[4:5]
	v_ashrrev_i32_e32 v19, 31, v18
	s_addc_u32 s9, s9, s11
	s_lshl_b32 s2, s13, 14
	v_readlane_b32 s17, v255, 6
	v_lshlrev_b64 v[2:3], 2, v[18:19]
	s_add_i32 s2, s2, 0
	v_lshl_add_u64 v[20:21], s[8:9], 0, v[2:3]
	v_lshl_add_u32 v68, v6, 3, s2
	s_lshl_b32 s2, s67, 6
	v_lshl_add_u64 v[2:3], s[16:17], 0, v[2:3]
	s_mov_b64 s[8:9], 0x800
	v_xor_b32_e32 v0, 4, v18
	v_xor_b32_e32 v30, 8, v18
	v_xor_b32_e32 v31, 16, v18
	v_xor_b32_e32 v32, 32, v18
	v_xor_b32_e32 v33, 64, v18
	v_xor_b32_e32 v34, 0x80, v18
	v_add_u32_e32 v36, 0x10000, v35
	v_add_u32_e32 v37, 0x10800, v35
	v_add_u32_e32 v38, 0x11000, v35
	v_add_u32_e32 v39, 0x11800, v35
	v_add_u32_e32 v40, 0x12000, v35
	v_add_u32_e32 v41, 0x12800, v35
	v_add_u32_e32 v42, 0x13000, v35
	v_add_u32_e32 v43, 0x13800, v35
	v_add_u32_e32 v44, 0x14000, v35
	v_add_u32_e32 v45, 0x14800, v35
	v_add_u32_e32 v46, 0x15000, v35
	v_add_u32_e32 v47, 0x15800, v35
	v_add_u32_e32 v48, 0x16000, v35
	v_add_u32_e32 v49, 0x16800, v35
	v_add_u32_e32 v50, 0x17000, v35
	v_add_u32_e32 v51, 0x17800, v35
	v_add_u32_e32 v52, 0x18000, v35
	v_add_u32_e32 v53, 0x18800, v35
	v_add_u32_e32 v54, 0x19000, v35
	v_add_u32_e32 v55, 0x19800, v35
	v_add_u32_e32 v56, 0x1a000, v35
	v_add_u32_e32 v57, 0x1a800, v35
	v_add_u32_e32 v58, 0x1b000, v35
	v_add_u32_e32 v59, 0x1b800, v35
	v_add_u32_e32 v60, 0x1c000, v35
	v_add_u32_e32 v61, 0x1c800, v35
	v_add_u32_e32 v62, 0x1d000, v35
	v_add_u32_e32 v63, 0x1d800, v35
	v_add_u32_e32 v64, 0x1e000, v35
	v_add_u32_e32 v65, 0x1e800, v35
	v_add_u32_e32 v66, 0x1f000, v35
	v_add_u32_e32 v67, 0x1f800, v35
	s_add_i32 s2, s2, s12
	v_lshl_add_u64 v[26:27], v[2:3], 0, s[8:9]
	s_and_b32 s0, s67, 7
	s_mul_i32 s0, s0, 6
	s_lshr_b32 s1, s67, 3
	s_mul_i32 s7, s1, 43
	s_lshr_b32 s7, s7, 8
	s_mul_i32 s3, s7, 6
	s_sub_i32 s1, s1, s3
	s_add_i32 s0, s0, s1
	s_lshl2_add_u32 s7, s0, s7
.LBB0_896:
	s_lshl_b32 s8, s7, 6
	v_readlane_b32 s9, v254, 63
	s_lshl_b32 s3, s9, 3
	s_add_i32 s16, s8, s3
	s_mov_b32 s17, 0
	s_sub_i32 s1, s8, 0x1800
	s_max_i32 s1, s1, 0
	s_lshr_b32 s1, s1, 11
	s_ashr_i32 s0, s80, 2
	s_and_b32 s6, s80, 3
	s_mul_i32 s3, s0, 3
	s_add_i32 s8, s3, s6
	v_readlane_b32 s10, v255, 14
	v_readlane_b32 s11, v255, 15
	s_load_dwordx2 s[12:13], s[10:11], 0x58
	s_add_i32 s3, s3, s1
	s_mul_i32 s3, s3, 0x9000
	s_mul_i32 s14, s6, 0x3000
	s_add_i32 s3, s3, s14
	s_add_i32 s3, s3, 0x100000
	v_readlane_b32 s18, v255, 7
	v_readlane_b32 s19, v255, 8
	s_add_u32 s18, s18, s3
	s_addc_u32 s19, s19, 0
	v_lshrrev_b32_e32 v200, 2, v18
	v_lshlrev_b32_e32 v201, 5, v200
	v_lshlrev_b32_e32 v202, 4, v200
	s_lshl_b32 s9, s9, 14
	v_add_u32_e32 v202, s9, v202
	s_lshl_b32 s8, s8, 12
	s_add_u32 s14, s18, 0x1000
	s_addc_u32 s15, s19, 0
	s_waitcnt lgkmcnt(0)
	s_add_u32 s12, s12, s8
	s_addc_u32 s13, s13, 0
	global_load_dwordx4 v[134:137], v201, s[12:13] offset:0
	global_load_dwordx4 v[150:153], v201, s[14:15] offset:0
	global_load_dwordx4 v[170:173], v201, s[18:19] offset:0
	global_load_dwordx4 v[138:141], v201, s[12:13] offset:16
	global_load_dwordx4 v[154:157], v201, s[14:15] offset:16
	global_load_dwordx4 v[174:177], v201, s[18:19] offset:16
	global_load_dwordx4 v[142:145], v201, s[12:13] offset:2048
	global_load_dwordx4 v[158:161], v201, s[14:15] offset:2048
	global_load_dwordx4 v[178:181], v201, s[18:19] offset:2048
	global_load_dwordx4 v[146:149], v201, s[12:13] offset:2064
	global_load_dwordx4 v[162:165], v201, s[14:15] offset:2064
	global_load_dwordx4 v[182:185], v201, s[18:19] offset:2064
	v_readlane_b32 s0, v254, 63
	s_cmp_lg_u32 s0, 0
	s_cbranch_scc1 .Lnt_bar
	s_lshr_b32 s0, s7, 2
	v_readlane_b32 s1, v254, 61
	s_add_i32 s1, s1, -1
	s_lshl_b32 s1, s1, 8
	s_lshl_b32 s0, s0, 2
	s_add_i32 s0, s0, s1
	s_add_i32 s0, s0, 0x10000
	v_readlane_b32 s10, v255, 7
	v_readlane_b32 s11, v255, 8
	s_add_u32 s10, s10, s0
	s_addc_u32 s11, s11, 0
	s_mov_b32 s0, 0
.Lnt_poll:
	global_load_dword v200, v1, s[10:11] sc1
	s_waitcnt vmcnt(0)
	v_readfirstlane_b32 s1, v200
	s_cmp_ge_u32 s1, 4
	s_cbranch_scc1 .Lnt_ok
	s_add_i32 s0, s0, 1
	s_cmp_gt_u32 s0, 0x20000
	s_cbranch_scc1 .Lnt_ok
	s_sleep 1
	s_branch .Lnt_poll

.Lnt_bar:
	s_barrier
	v_readlane_b32 s10, v255, 5
	v_readlane_b32 s11, v255, 6
	s_lshl_b64 s[12:13], s[16:17], 12
	s_add_u32 s10, s10, s12
	s_addc_u32 s11, s11, s13
	s_mov_b32 s3, 0x3a800000
	global_load_dwordx4 v[70:73], v201, s[10:11] offset:0
	global_load_dwordx4 v[74:77], v201, s[10:11] offset:16
	global_load_dwordx4 v[78:81], v201, s[10:11] offset:2048
	global_load_dwordx4 v[82:85], v201, s[10:11] offset:2064
	s_add_u32 s10, s10, 0x1000
	s_addc_u32 s11, s11, 0
	global_load_dwordx4 v[86:89], v201, s[10:11] offset:0
	global_load_dwordx4 v[90:93], v201, s[10:11] offset:16
	global_load_dwordx4 v[94:97], v201, s[10:11] offset:2048
	global_load_dwordx4 v[98:101], v201, s[10:11] offset:2064
	s_add_u32 s10, s10, 0x1000
	s_addc_u32 s11, s11, 0
	global_load_dwordx4 v[102:105], v201, s[10:11] offset:0
	global_load_dwordx4 v[106:109], v201, s[10:11] offset:16
	global_load_dwordx4 v[110:113], v201, s[10:11] offset:2048
	global_load_dwordx4 v[114:117], v201, s[10:11] offset:2064
	s_add_u32 s10, s10, 0x1000
	s_addc_u32 s11, s11, 0
	global_load_dwordx4 v[118:121], v201, s[10:11] offset:0
	global_load_dwordx4 v[122:125], v201, s[10:11] offset:16
	global_load_dwordx4 v[126:129], v201, s[10:11] offset:2048
	global_load_dwordx4 v[130:133], v201, s[10:11] offset:2064
	s_add_u32 s10, s10, 0x1000
	s_addc_u32 s11, s11, 0
	s_waitcnt vmcnt(16)
	v_add_f32_e32 v150, 1.0, v150
	v_add_f32_e32 v151, 1.0, v151
	v_add_f32_e32 v152, 1.0, v152
	v_add_f32_e32 v153, 1.0, v153
	v_add_f32_e32 v154, 1.0, v154
	v_add_f32_e32 v155, 1.0, v155
	v_add_f32_e32 v156, 1.0, v156
	v_add_f32_e32 v157, 1.0, v157
	v_add_f32_e32 v158, 1.0, v158
	v_add_f32_e32 v159, 1.0, v159
	v_add_f32_e32 v160, 1.0, v160
	v_add_f32_e32 v161, 1.0, v161
	v_add_f32_e32 v162, 1.0, v162
	v_add_f32_e32 v163, 1.0, v163
	v_add_f32_e32 v164, 1.0, v164
	v_add_f32_e32 v165, 1.0, v165
	v_mul_f32_e32 v150, v134, v150
	v_mul_f32_e32 v151, v135, v151
	v_mul_f32_e32 v152, v136, v152
	v_mul_f32_e32 v153, v137, v153
	v_mul_f32_e32 v154, v138, v154
	v_mul_f32_e32 v155, v139, v155
	v_mul_f32_e32 v156, v140, v156
	v_mul_f32_e32 v157, v141, v157
	v_mul_f32_e32 v158, v142, v158
	v_mul_f32_e32 v159, v143, v159
	v_mul_f32_e32 v160, v144, v160
	v_mul_f32_e32 v161, v145, v161
	v_mul_f32_e32 v162, v146, v162
	v_mul_f32_e32 v163, v147, v163
	v_mul_f32_e32 v164, v148, v164
	v_mul_f32_e32 v165, v149, v165
	s_waitcnt vmcnt(12)
	v_mul_f32_e32 v186, v70, v70
	v_fmac_f32_e32 v186, v71, v71
	v_fmac_f32_e32 v186, v72, v72
	v_fmac_f32_e32 v186, v73, v73
	v_fmac_f32_e32 v186, v74, v74
	v_fmac_f32_e32 v186, v75, v75
	v_fmac_f32_e32 v186, v76, v76
	v_fmac_f32_e32 v186, v77, v77
	v_fmac_f32_e32 v186, v78, v78
	v_fmac_f32_e32 v186, v79, v79
	v_fmac_f32_e32 v186, v80, v80
	v_fmac_f32_e32 v186, v81, v81
	v_fmac_f32_e32 v186, v82, v82
	v_fmac_f32_e32 v186, v83, v83
	v_fmac_f32_e32 v186, v84, v84
	v_fmac_f32_e32 v186, v85, v85
	s_waitcnt vmcnt(8)
	v_mul_f32_e32 v187, v86, v86
	v_fmac_f32_e32 v187, v87, v87
	v_fmac_f32_e32 v187, v88, v88
	v_fmac_f32_e32 v187, v89, v89
	v_fmac_f32_e32 v187, v90, v90
	v_fmac_f32_e32 v187, v91, v91
	v_fmac_f32_e32 v187, v92, v92
	v_fmac_f32_e32 v187, v93, v93
	v_fmac_f32_e32 v187, v94, v94
	v_fmac_f32_e32 v187, v95, v95
	v_fmac_f32_e32 v187, v96, v96
	v_fmac_f32_e32 v187, v97, v97
	v_fmac_f32_e32 v187, v98, v98
	v_fmac_f32_e32 v187, v99, v99
	v_fmac_f32_e32 v187, v100, v100
	v_fmac_f32_e32 v187, v101, v101
	s_waitcnt vmcnt(4)
	v_mul_f32_e32 v188, v102, v102
	v_fmac_f32_e32 v188, v103, v103
	v_fmac_f32_e32 v188, v104, v104
	v_fmac_f32_e32 v188, v105, v105
	v_fmac_f32_e32 v188, v106, v106
	v_fmac_f32_e32 v188, v107, v107
	v_fmac_f32_e32 v188, v108, v108
	v_fmac_f32_e32 v188, v109, v109
	v_fmac_f32_e32 v188, v110, v110
	v_fmac_f32_e32 v188, v111, v111
	v_fmac_f32_e32 v188, v112, v112
	v_fmac_f32_e32 v188, v113, v113
	v_fmac_f32_e32 v188, v114, v114
	v_fmac_f32_e32 v188, v115, v115
	v_fmac_f32_e32 v188, v116, v116
	v_fmac_f32_e32 v188, v117, v117
	s_waitcnt vmcnt(0)
	v_mul_f32_e32 v189, v118, v118
	v_fmac_f32_e32 v189, v119, v119
	v_fmac_f32_e32 v189, v120, v120
	v_fmac_f32_e32 v189, v121, v121
	v_fmac_f32_e32 v189, v122, v122
	v_fmac_f32_e32 v189, v123, v123
	v_fmac_f32_e32 v189, v124, v124
	v_fmac_f32_e32 v189, v125, v125
	v_fmac_f32_e32 v189, v126, v126
	v_fmac_f32_e32 v189, v127, v127
	v_fmac_f32_e32 v189, v128, v128
	v_fmac_f32_e32 v189, v129, v129
	v_fmac_f32_e32 v189, v130, v130
	v_fmac_f32_e32 v189, v131, v131
	v_fmac_f32_e32 v189, v132, v132
	v_fmac_f32_e32 v189, v133, v133
	s_nop 1
	v_add_f32_dpp v186, v186, v186 row_ror:8 row_mask:0xf bank_mask:0xf
	v_add_f32_dpp v187, v187, v187 row_ror:8 row_mask:0xf bank_mask:0xf
	v_add_f32_dpp v188, v188, v188 row_ror:8 row_mask:0xf bank_mask:0xf
	v_add_f32_dpp v189, v189, v189 row_ror:8 row_mask:0xf bank_mask:0xf
	v_add_f32_dpp v186, v186, v186 row_ror:4 row_mask:0xf bank_mask:0xf
	v_add_f32_dpp v187, v187, v187 row_ror:4 row_mask:0xf bank_mask:0xf
	v_add_f32_dpp v188, v188, v188 row_ror:4 row_mask:0xf bank_mask:0xf
	v_add_f32_dpp v189, v189, v189 row_ror:4 row_mask:0xf bank_mask:0xf
	v_add_f32_dpp v186, v186, v186 row_ror:2 row_mask:0xf bank_mask:0xf
	v_add_f32_dpp v187, v187, v187 row_ror:2 row_mask:0xf bank_mask:0xf
	v_add_f32_dpp v188, v188, v188 row_ror:2 row_mask:0xf bank_mask:0xf
	v_add_f32_dpp v189, v189, v189 row_ror:2 row_mask:0xf bank_mask:0xf
	v_add_f32_dpp v186, v186, v186 row_ror:1 row_mask:0xf bank_mask:0xf
	v_add_f32_dpp v187, v187, v187 row_ror:1 row_mask:0xf bank_mask:0xf
	v_add_f32_dpp v188, v188, v188 row_ror:1 row_mask:0xf bank_mask:0xf
	v_add_f32_dpp v189, v189, v189 row_ror:1 row_mask:0xf bank_mask:0xf
	v_mov_b32_e32 v190, v186
	v_mov_b32_e32 v191, v187
	v_mov_b32_e32 v192, v188
	v_mov_b32_e32 v193, v189
	s_nop 1
	v_permlane16_swap_b32_e32 v190, v186
	v_permlane16_swap_b32_e32 v191, v187
	v_permlane16_swap_b32_e32 v192, v188
	v_permlane16_swap_b32_e32 v193, v189
	v_add_f32_e32 v186, v186, v190
	v_add_f32_e32 v187, v187, v191
	v_add_f32_e32 v188, v188, v192
	v_add_f32_e32 v189, v189, v193
	v_mov_b32_e32 v190, v186
	v_mov_b32_e32 v191, v187
	v_mov_b32_e32 v192, v188
	v_mov_b32_e32 v193, v189
	s_nop 1
	v_permlane32_swap_b32_e32 v190, v186
	v_permlane32_swap_b32_e32 v191, v187
	v_permlane32_swap_b32_e32 v192, v188
	v_permlane32_swap_b32_e32 v193, v189
	v_add_f32_e32 v186, v186, v190
	v_add_f32_e32 v187, v187, v191
	v_add_f32_e32 v188, v188, v192
	v_add_f32_e32 v189, v189, v193
	v_fma_f32 v186, v186, s3, v167
	v_fma_f32 v187, v187, s3, v167
	v_fma_f32 v188, v188, s3, v167
	v_fma_f32 v189, v189, s3, v167
	v_rsq_f32_e32 v186, v186
	v_rsq_f32_e32 v187, v187
	v_rsq_f32_e32 v188, v188
	v_rsq_f32_e32 v189, v189
	s_nop 0
	v_mul_f32_e32 v70, v70, v186
	v_mul_f32_e32 v71, v71, v186
	v_mul_f32_e32 v72, v72, v186
	v_mul_f32_e32 v73, v73, v186
	v_mul_f32_e32 v74, v74, v186
	v_mul_f32_e32 v75, v75, v186
	v_mul_f32_e32 v76, v76, v186
	v_mul_f32_e32 v77, v77, v186
	v_mul_f32_e32 v78, v78, v186
	v_mul_f32_e32 v79, v79, v186
	v_mul_f32_e32 v80, v80, v186
	v_mul_f32_e32 v81, v81, v186
	v_mul_f32_e32 v82, v82, v186
	v_mul_f32_e32 v83, v83, v186
	v_mul_f32_e32 v84, v84, v186
	v_mul_f32_e32 v85, v85, v186
	v_fma_f32 v70, v70, v150, v170
	v_fma_f32 v71, v71, v151, v171
	v_fma_f32 v72, v72, v152, v172
	v_fma_f32 v73, v73, v153, v173
	v_fma_f32 v74, v74, v154, v174
	v_fma_f32 v75, v75, v155, v175
	v_fma_f32 v76, v76, v156, v176
	v_fma_f32 v77, v77, v157, v177
	v_fma_f32 v78, v78, v158, v178
	v_fma_f32 v79, v79, v159, v179
	v_fma_f32 v80, v80, v160, v180
	v_fma_f32 v81, v81, v161, v181
	v_fma_f32 v82, v82, v162, v182
	v_fma_f32 v83, v83, v163, v183
	v_fma_f32 v84, v84, v164, v184
	v_fma_f32 v85, v85, v165, v185
	v_cvt_pk_bf16_f32 v70, v70, v71
	v_cvt_pk_bf16_f32 v71, v72, v73
	v_cvt_pk_bf16_f32 v72, v74, v75
	v_cvt_pk_bf16_f32 v73, v76, v77
	v_cvt_pk_bf16_f32 v78, v78, v79
	v_cvt_pk_bf16_f32 v79, v80, v81
	v_cvt_pk_bf16_f32 v80, v82, v83
	v_cvt_pk_bf16_f32 v81, v84, v85
	ds_write_b128 v202, v[70:73] offset:0
	ds_write_b128 v202, v[78:81] offset:1024
	v_mul_f32_e32 v86, v86, v187
	v_mul_f32_e32 v87, v87, v187
	v_mul_f32_e32 v88, v88, v187
	v_mul_f32_e32 v89, v89, v187
	v_mul_f32_e32 v90, v90, v187
	v_mul_f32_e32 v91, v91, v187
	v_mul_f32_e32 v92, v92, v187
	v_mul_f32_e32 v93, v93, v187
	v_mul_f32_e32 v94, v94, v187
	v_mul_f32_e32 v95, v95, v187
	v_mul_f32_e32 v96, v96, v187
	v_mul_f32_e32 v97, v97, v187
	v_mul_f32_e32 v98, v98, v187
	v_mul_f32_e32 v99, v99, v187
	v_mul_f32_e32 v100, v100, v187
	v_mul_f32_e32 v101, v101, v187
	v_fma_f32 v86, v86, v150, v170
	v_fma_f32 v87, v87, v151, v171
	v_fma_f32 v88, v88, v152, v172
	v_fma_f32 v89, v89, v153, v173
	v_fma_f32 v90, v90, v154, v174
	v_fma_f32 v91, v91, v155, v175
	v_fma_f32 v92, v92, v156, v176
	v_fma_f32 v93, v93, v157, v177
	v_fma_f32 v94, v94, v158, v178
	v_fma_f32 v95, v95, v159, v179
	v_fma_f32 v96, v96, v160, v180
	v_fma_f32 v97, v97, v161, v181
	v_fma_f32 v98, v98, v162, v182
	v_fma_f32 v99, v99, v163, v183
	v_fma_f32 v100, v100, v164, v184
	v_fma_f32 v101, v101, v165, v185
	v_cvt_pk_bf16_f32 v86, v86, v87
	v_cvt_pk_bf16_f32 v87, v88, v89
	v_cvt_pk_bf16_f32 v88, v90, v91
	v_cvt_pk_bf16_f32 v89, v92, v93
	v_cvt_pk_bf16_f32 v94, v94, v95
	v_cvt_pk_bf16_f32 v95, v96, v97
	v_cvt_pk_bf16_f32 v96, v98, v99
	v_cvt_pk_bf16_f32 v97, v100, v101
	ds_write_b128 v202, v[86:89] offset:2048
	ds_write_b128 v202, v[94:97] offset:3072
	v_mul_f32_e32 v102, v102, v188
	v_mul_f32_e32 v103, v103, v188
	v_mul_f32_e32 v104, v104, v188
	v_mul_f32_e32 v105, v105, v188
	v_mul_f32_e32 v106, v106, v188
	v_mul_f32_e32 v107, v107, v188
	v_mul_f32_e32 v108, v108, v188
	v_mul_f32_e32 v109, v109, v188
	v_mul_f32_e32 v110, v110, v188
	v_mul_f32_e32 v111, v111, v188
	v_mul_f32_e32 v112, v112, v188
	v_mul_f32_e32 v113, v113, v188
	v_mul_f32_e32 v114, v114, v188
	v_mul_f32_e32 v115, v115, v188
	v_mul_f32_e32 v116, v116, v188
	v_mul_f32_e32 v117, v117, v188
	v_fma_f32 v102, v102, v150, v170
	v_fma_f32 v103, v103, v151, v171
	v_fma_f32 v104, v104, v152, v172
	v_fma_f32 v105, v105, v153, v173
	v_fma_f32 v106, v106, v154, v174
	v_fma_f32 v107, v107, v155, v175
	v_fma_f32 v108, v108, v156, v176
	v_fma_f32 v109, v109, v157, v177
	v_fma_f32 v110, v110, v158, v178
	v_fma_f32 v111, v111, v159, v179
	v_fma_f32 v112, v112, v160, v180
	v_fma_f32 v113, v113, v161, v181
	v_fma_f32 v114, v114, v162, v182
	v_fma_f32 v115, v115, v163, v183
	v_fma_f32 v116, v116, v164, v184
	v_fma_f32 v117, v117, v165, v185
	v_cvt_pk_bf16_f32 v102, v102, v103
	v_cvt_pk_bf16_f32 v103, v104, v105
	v_cvt_pk_bf16_f32 v104, v106, v107
	v_cvt_pk_bf16_f32 v105, v108, v109
	v_cvt_pk_bf16_f32 v110, v110, v111
	v_cvt_pk_bf16_f32 v111, v112, v113
	v_cvt_pk_bf16_f32 v112, v114, v115
	v_cvt_pk_bf16_f32 v113, v116, v117
	ds_write_b128 v202, v[102:105] offset:4096
	ds_write_b128 v202, v[110:113] offset:5120
	v_mul_f32_e32 v118, v118, v189
	v_mul_f32_e32 v119, v119, v189
	v_mul_f32_e32 v120, v120, v189
	v_mul_f32_e32 v121, v121, v189
	v_mul_f32_e32 v122, v122, v189
	v_mul_f32_e32 v123, v123, v189
	v_mul_f32_e32 v124, v124, v189
	v_mul_f32_e32 v125, v125, v189
	v_mul_f32_e32 v126, v126, v189
	v_mul_f32_e32 v127, v127, v189
	v_mul_f32_e32 v128, v128, v189
	v_mul_f32_e32 v129, v129, v189
	v_mul_f32_e32 v130, v130, v189
	v_mul_f32_e32 v131, v131, v189
	v_mul_f32_e32 v132, v132, v189
	v_mul_f32_e32 v133, v133, v189
	v_fma_f32 v118, v118, v150, v170
	v_fma_f32 v119, v119, v151, v171
	v_fma_f32 v120, v120, v152, v172
	v_fma_f32 v121, v121, v153, v173
	v_fma_f32 v122, v122, v154, v174
	v_fma_f32 v123, v123, v155, v175
	v_fma_f32 v124, v124, v156, v176
	v_fma_f32 v125, v125, v157, v177
	v_fma_f32 v126, v126, v158, v178
	v_fma_f32 v127, v127, v159, v179
	v_fma_f32 v128, v128, v160, v180
	v_fma_f32 v129, v129, v161, v181
	v_fma_f32 v130, v130, v162, v182
	v_fma_f32 v131, v131, v163, v183
	v_fma_f32 v132, v132, v164, v184
	v_fma_f32 v133, v133, v165, v185
	v_cvt_pk_bf16_f32 v118, v118, v119
	v_cvt_pk_bf16_f32 v119, v120, v121
	v_cvt_pk_bf16_f32 v120, v122, v123
	v_cvt_pk_bf16_f32 v121, v124, v125
	v_cvt_pk_bf16_f32 v126, v126, v127
	v_cvt_pk_bf16_f32 v127, v128, v129
	v_cvt_pk_bf16_f32 v128, v130, v131
	v_cvt_pk_bf16_f32 v129, v132, v133
	ds_write_b128 v202, v[118:121] offset:6144
	ds_write_b128 v202, v[126:129] offset:7168
	global_load_dwordx4 v[70:73], v201, s[10:11] offset:0
	global_load_dwordx4 v[74:77], v201, s[10:11] offset:16
	global_load_dwordx4 v[78:81], v201, s[10:11] offset:2048
	global_load_dwordx4 v[82:85], v201, s[10:11] offset:2064
	s_add_u32 s10, s10, 0x1000
	s_addc_u32 s11, s11, 0
	global_load_dwordx4 v[86:89], v201, s[10:11] offset:0
	global_load_dwordx4 v[90:93], v201, s[10:11] offset:16
	global_load_dwordx4 v[94:97], v201, s[10:11] offset:2048
	global_load_dwordx4 v[98:101], v201, s[10:11] offset:2064
	s_add_u32 s10, s10, 0x1000
	s_addc_u32 s11, s11, 0
	global_load_dwordx4 v[102:105], v201, s[10:11] offset:0
	global_load_dwordx4 v[106:109], v201, s[10:11] offset:16
	global_load_dwordx4 v[110:113], v201, s[10:11] offset:2048
	global_load_dwordx4 v[114:117], v201, s[10:11] offset:2064
	s_add_u32 s10, s10, 0x1000
	s_addc_u32 s11, s11, 0
	global_load_dwordx4 v[118:121], v201, s[10:11] offset:0
	global_load_dwordx4 v[122:125], v201, s[10:11] offset:16
	global_load_dwordx4 v[126:129], v201, s[10:11] offset:2048
	global_load_dwordx4 v[130:133], v201, s[10:11] offset:2064
	s_add_u32 s10, s10, 0x1000
	s_addc_u32 s11, s11, 0
	s_waitcnt vmcnt(12)
	v_mul_f32_e32 v186, v70, v70
	v_fmac_f32_e32 v186, v71, v71
	v_fmac_f32_e32 v186, v72, v72
	v_fmac_f32_e32 v186, v73, v73
	v_fmac_f32_e32 v186, v74, v74
	v_fmac_f32_e32 v186, v75, v75
	v_fmac_f32_e32 v186, v76, v76
	v_fmac_f32_e32 v186, v77, v77
	v_fmac_f32_e32 v186, v78, v78
	v_fmac_f32_e32 v186, v79, v79
	v_fmac_f32_e32 v186, v80, v80
	v_fmac_f32_e32 v186, v81, v81
	v_fmac_f32_e32 v186, v82, v82
	v_fmac_f32_e32 v186, v83, v83
	v_fmac_f32_e32 v186, v84, v84
	v_fmac_f32_e32 v186, v85, v85
	s_waitcnt vmcnt(8)
	v_mul_f32_e32 v187, v86, v86
	v_fmac_f32_e32 v187, v87, v87
	v_fmac_f32_e32 v187, v88, v88
	v_fmac_f32_e32 v187, v89, v89
	v_fmac_f32_e32 v187, v90, v90
	v_fmac_f32_e32 v187, v91, v91
	v_fmac_f32_e32 v187, v92, v92
	v_fmac_f32_e32 v187, v93, v93
	v_fmac_f32_e32 v187, v94, v94
	v_fmac_f32_e32 v187, v95, v95
	v_fmac_f32_e32 v187, v96, v96
	v_fmac_f32_e32 v187, v97, v97
	v_fmac_f32_e32 v187, v98, v98
	v_fmac_f32_e32 v187, v99, v99
	v_fmac_f32_e32 v187, v100, v100
	v_fmac_f32_e32 v187, v101, v101
	s_waitcnt vmcnt(4)
	v_mul_f32_e32 v188, v102, v102
	v_fmac_f32_e32 v188, v103, v103
	v_fmac_f32_e32 v188, v104, v104
	v_fmac_f32_e32 v188, v105, v105
	v_fmac_f32_e32 v188, v106, v106
	v_fmac_f32_e32 v188, v107, v107
	v_fmac_f32_e32 v188, v108, v108
	v_fmac_f32_e32 v188, v109, v109
	v_fmac_f32_e32 v188, v110, v110
	v_fmac_f32_e32 v188, v111, v111
	v_fmac_f32_e32 v188, v112, v112
	v_fmac_f32_e32 v188, v113, v113
	v_fmac_f32_e32 v188, v114, v114
	v_fmac_f32_e32 v188, v115, v115
	v_fmac_f32_e32 v188, v116, v116
	v_fmac_f32_e32 v188, v117, v117
	s_waitcnt vmcnt(0)
	v_mul_f32_e32 v189, v118, v118
	v_fmac_f32_e32 v189, v119, v119
	v_fmac_f32_e32 v189, v120, v120
	v_fmac_f32_e32 v189, v121, v121
	v_fmac_f32_e32 v189, v122, v122
	v_fmac_f32_e32 v189, v123, v123
	v_fmac_f32_e32 v189, v124, v124
	v_fmac_f32_e32 v189, v125, v125
	v_fmac_f32_e32 v189, v126, v126
	v_fmac_f32_e32 v189, v127, v127
	v_fmac_f32_e32 v189, v128, v128
	v_fmac_f32_e32 v189, v129, v129
	v_fmac_f32_e32 v189, v130, v130
	v_fmac_f32_e32 v189, v131, v131
	v_fmac_f32_e32 v189, v132, v132
	v_fmac_f32_e32 v189, v133, v133
	s_nop 1
	v_add_f32_dpp v186, v186, v186 row_ror:8 row_mask:0xf bank_mask:0xf
	v_add_f32_dpp v187, v187, v187 row_ror:8 row_mask:0xf bank_mask:0xf
	v_add_f32_dpp v188, v188, v188 row_ror:8 row_mask:0xf bank_mask:0xf
	v_add_f32_dpp v189, v189, v189 row_ror:8 row_mask:0xf bank_mask:0xf
	v_add_f32_dpp v186, v186, v186 row_ror:4 row_mask:0xf bank_mask:0xf
	v_add_f32_dpp v187, v187, v187 row_ror:4 row_mask:0xf bank_mask:0xf
	v_add_f32_dpp v188, v188, v188 row_ror:4 row_mask:0xf bank_mask:0xf
	v_add_f32_dpp v189, v189, v189 row_ror:4 row_mask:0xf bank_mask:0xf
	v_add_f32_dpp v186, v186, v186 row_ror:2 row_mask:0xf bank_mask:0xf
	v_add_f32_dpp v187, v187, v187 row_ror:2 row_mask:0xf bank_mask:0xf
	v_add_f32_dpp v188, v188, v188 row_ror:2 row_mask:0xf bank_mask:0xf
	v_add_f32_dpp v189, v189, v189 row_ror:2 row_mask:0xf bank_mask:0xf
	v_add_f32_dpp v186, v186, v186 row_ror:1 row_mask:0xf bank_mask:0xf
	v_add_f32_dpp v187, v187, v187 row_ror:1 row_mask:0xf bank_mask:0xf
	v_add_f32_dpp v188, v188, v188 row_ror:1 row_mask:0xf bank_mask:0xf
	v_add_f32_dpp v189, v189, v189 row_ror:1 row_mask:0xf bank_mask:0xf
	v_mov_b32_e32 v190, v186
	v_mov_b32_e32 v191, v187
	v_mov_b32_e32 v192, v188
	v_mov_b32_e32 v193, v189
	s_nop 1
	v_permlane16_swap_b32_e32 v190, v186
	v_permlane16_swap_b32_e32 v191, v187
	v_permlane16_swap_b32_e32 v192, v188
	v_permlane16_swap_b32_e32 v193, v189
	v_add_f32_e32 v186, v186, v190
	v_add_f32_e32 v187, v187, v191
	v_add_f32_e32 v188, v188, v192
	v_add_f32_e32 v189, v189, v193
	v_mov_b32_e32 v190, v186
	v_mov_b32_e32 v191, v187
	v_mov_b32_e32 v192, v188
	v_mov_b32_e32 v193, v189
	s_nop 1
	v_permlane32_swap_b32_e32 v190, v186
	v_permlane32_swap_b32_e32 v191, v187
	v_permlane32_swap_b32_e32 v192, v188
	v_permlane32_swap_b32_e32 v193, v189
	v_add_f32_e32 v186, v186, v190
	v_add_f32_e32 v187, v187, v191
	v_add_f32_e32 v188, v188, v192
	v_add_f32_e32 v189, v189, v193
	v_fma_f32 v186, v186, s3, v167
	v_fma_f32 v187, v187, s3, v167
	v_fma_f32 v188, v188, s3, v167
	v_fma_f32 v189, v189, s3, v167
	v_rsq_f32_e32 v186, v186
	v_rsq_f32_e32 v187, v187
	v_rsq_f32_e32 v188, v188
	v_rsq_f32_e32 v189, v189
	s_nop 0
	v_mul_f32_e32 v70, v70, v186
	v_mul_f32_e32 v71, v71, v186
	v_mul_f32_e32 v72, v72, v186
	v_mul_f32_e32 v73, v73, v186
	v_mul_f32_e32 v74, v74, v186
	v_mul_f32_e32 v75, v75, v186
	v_mul_f32_e32 v76, v76, v186
	v_mul_f32_e32 v77, v77, v186
	v_mul_f32_e32 v78, v78, v186
	v_mul_f32_e32 v79, v79, v186
	v_mul_f32_e32 v80, v80, v186
	v_mul_f32_e32 v81, v81, v186
	v_mul_f32_e32 v82, v82, v186
	v_mul_f32_e32 v83, v83, v186
	v_mul_f32_e32 v84, v84, v186
	v_mul_f32_e32 v85, v85, v186
	v_fma_f32 v70, v70, v150, v170
	v_fma_f32 v71, v71, v151, v171
	v_fma_f32 v72, v72, v152, v172
	v_fma_f32 v73, v73, v153, v173
	v_fma_f32 v74, v74, v154, v174
	v_fma_f32 v75, v75, v155, v175
	v_fma_f32 v76, v76, v156, v176
	v_fma_f32 v77, v77, v157, v177
	v_fma_f32 v78, v78, v158, v178
	v_fma_f32 v79, v79, v159, v179
	v_fma_f32 v80, v80, v160, v180
	v_fma_f32 v81, v81, v161, v181
	v_fma_f32 v82, v82, v162, v182
	v_fma_f32 v83, v83, v163, v183
	v_fma_f32 v84, v84, v164, v184
	v_fma_f32 v85, v85, v165, v185
	v_cvt_pk_bf16_f32 v70, v70, v71
	v_cvt_pk_bf16_f32 v71, v72, v73
	v_cvt_pk_bf16_f32 v72, v74, v75
	v_cvt_pk_bf16_f32 v73, v76, v77
	v_cvt_pk_bf16_f32 v78, v78, v79
	v_cvt_pk_bf16_f32 v79, v80, v81
	v_cvt_pk_bf16_f32 v80, v82, v83
	v_cvt_pk_bf16_f32 v81, v84, v85
	ds_write_b128 v202, v[70:73] offset:8192
	ds_write_b128 v202, v[78:81] offset:9216
	v_mul_f32_e32 v86, v86, v187
	v_mul_f32_e32 v87, v87, v187
	v_mul_f32_e32 v88, v88, v187
	v_mul_f32_e32 v89, v89, v187
	v_mul_f32_e32 v90, v90, v187
	v_mul_f32_e32 v91, v91, v187
	v_mul_f32_e32 v92, v92, v187
	v_mul_f32_e32 v93, v93, v187
	v_mul_f32_e32 v94, v94, v187
	v_mul_f32_e32 v95, v95, v187
	v_mul_f32_e32 v96, v96, v187
	v_mul_f32_e32 v97, v97, v187
	v_mul_f32_e32 v98, v98, v187
	v_mul_f32_e32 v99, v99, v187
	v_mul_f32_e32 v100, v100, v187
	v_mul_f32_e32 v101, v101, v187
	v_fma_f32 v86, v86, v150, v170
	v_fma_f32 v87, v87, v151, v171
	v_fma_f32 v88, v88, v152, v172
	v_fma_f32 v89, v89, v153, v173
	v_fma_f32 v90, v90, v154, v174
	v_fma_f32 v91, v91, v155, v175
	v_fma_f32 v92, v92, v156, v176
	v_fma_f32 v93, v93, v157, v177
	v_fma_f32 v94, v94, v158, v178
	v_fma_f32 v95, v95, v159, v179
	v_fma_f32 v96, v96, v160, v180
	v_fma_f32 v97, v97, v161, v181
	v_fma_f32 v98, v98, v162, v182
	v_fma_f32 v99, v99, v163, v183
	v_fma_f32 v100, v100, v164, v184
	v_fma_f32 v101, v101, v165, v185
	v_cvt_pk_bf16_f32 v86, v86, v87
	v_cvt_pk_bf16_f32 v87, v88, v89
	v_cvt_pk_bf16_f32 v88, v90, v91
	v_cvt_pk_bf16_f32 v89, v92, v93
	v_cvt_pk_bf16_f32 v94, v94, v95
	v_cvt_pk_bf16_f32 v95, v96, v97
	v_cvt_pk_bf16_f32 v96, v98, v99
	v_cvt_pk_bf16_f32 v97, v100, v101
	ds_write_b128 v202, v[86:89] offset:10240
	ds_write_b128 v202, v[94:97] offset:11264
	v_mul_f32_e32 v102, v102, v188
	v_mul_f32_e32 v103, v103, v188
	v_mul_f32_e32 v104, v104, v188
	v_mul_f32_e32 v105, v105, v188
	v_mul_f32_e32 v106, v106, v188
	v_mul_f32_e32 v107, v107, v188
	v_mul_f32_e32 v108, v108, v188
	v_mul_f32_e32 v109, v109, v188
	v_mul_f32_e32 v110, v110, v188
	v_mul_f32_e32 v111, v111, v188
	v_mul_f32_e32 v112, v112, v188
	v_mul_f32_e32 v113, v113, v188
	v_mul_f32_e32 v114, v114, v188
	v_mul_f32_e32 v115, v115, v188
	v_mul_f32_e32 v116, v116, v188
	v_mul_f32_e32 v117, v117, v188
	v_fma_f32 v102, v102, v150, v170
	v_fma_f32 v103, v103, v151, v171
	v_fma_f32 v104, v104, v152, v172
	v_fma_f32 v105, v105, v153, v173
	v_fma_f32 v106, v106, v154, v174
	v_fma_f32 v107, v107, v155, v175
	v_fma_f32 v108, v108, v156, v176
	v_fma_f32 v109, v109, v157, v177
	v_fma_f32 v110, v110, v158, v178
	v_fma_f32 v111, v111, v159, v179
	v_fma_f32 v112, v112, v160, v180
	v_fma_f32 v113, v113, v161, v181
	v_fma_f32 v114, v114, v162, v182
	v_fma_f32 v115, v115, v163, v183
	v_fma_f32 v116, v116, v164, v184
	v_fma_f32 v117, v117, v165, v185
	v_cvt_pk_bf16_f32 v102, v102, v103
	v_cvt_pk_bf16_f32 v103, v104, v105
	v_cvt_pk_bf16_f32 v104, v106, v107
	v_cvt_pk_bf16_f32 v105, v108, v109
	v_cvt_pk_bf16_f32 v110, v110, v111
	v_cvt_pk_bf16_f32 v111, v112, v113
	v_cvt_pk_bf16_f32 v112, v114, v115
	v_cvt_pk_bf16_f32 v113, v116, v117
	ds_write_b128 v202, v[102:105] offset:12288
	ds_write_b128 v202, v[110:113] offset:13312
	v_mul_f32_e32 v118, v118, v189
	v_mul_f32_e32 v119, v119, v189
	v_mul_f32_e32 v120, v120, v189
	v_mul_f32_e32 v121, v121, v189
	v_mul_f32_e32 v122, v122, v189
	v_mul_f32_e32 v123, v123, v189
	v_mul_f32_e32 v124, v124, v189
	v_mul_f32_e32 v125, v125, v189
	v_mul_f32_e32 v126, v126, v189
	v_mul_f32_e32 v127, v127, v189
	v_mul_f32_e32 v128, v128, v189
	v_mul_f32_e32 v129, v129, v189
	v_mul_f32_e32 v130, v130, v189
	v_mul_f32_e32 v131, v131, v189
	v_mul_f32_e32 v132, v132, v189
	v_mul_f32_e32 v133, v133, v189
	v_fma_f32 v118, v118, v150, v170
	v_fma_f32 v119, v119, v151, v171
	v_fma_f32 v120, v120, v152, v172
	v_fma_f32 v121, v121, v153, v173
	v_fma_f32 v122, v122, v154, v174
	v_fma_f32 v123, v123, v155, v175
	v_fma_f32 v124, v124, v156, v176
	v_fma_f32 v125, v125, v157, v177
	v_fma_f32 v126, v126, v158, v178
	v_fma_f32 v127, v127, v159, v179
	v_fma_f32 v128, v128, v160, v180
	v_fma_f32 v129, v129, v161, v181
	v_fma_f32 v130, v130, v162, v182
	v_fma_f32 v131, v131, v163, v183
	v_fma_f32 v132, v132, v164, v184
	v_fma_f32 v133, v133, v165, v185
	v_cvt_pk_bf16_f32 v118, v118, v119
	v_cvt_pk_bf16_f32 v119, v120, v121
	v_cvt_pk_bf16_f32 v120, v122, v123
	v_cvt_pk_bf16_f32 v121, v124, v125
	v_cvt_pk_bf16_f32 v126, v126, v127
	v_cvt_pk_bf16_f32 v127, v128, v129
	v_cvt_pk_bf16_f32 v128, v130, v131
	v_cvt_pk_bf16_f32 v129, v132, v133
	ds_write_b128 v202, v[118:121] offset:14336
	ds_write_b128 v202, v[126:129] offset:15360
	s_waitcnt lgkmcnt(0)
	s_barrier
	ds_read2st64_b32 v[10:11], v35 offset1:8
	ds_read2st64_b32 v[12:13], v35 offset0:16 offset1:24
	ds_read2st64_b32 v[14:15], v35 offset0:32 offset1:40
	ds_read2st64_b32 v[16:17], v35 offset0:48 offset1:56
	s_lshl_b32 s8, s7, 6
	s_ashr_i32 s9, s8, 31
	s_waitcnt lgkmcnt(2)
	v_and_b32_e32 v7, 0xffff, v12
	v_and_b32_e32 v6, 0xffff, v10
	v_lshrrev_b32_e32 v10, 16, v10
	v_lshl_or_b32 v6, v11, 16, v6
	v_and_or_b32 v10, v11, s91, v10
	v_lshrrev_b32_e32 v11, 16, v12
	s_lshl_b64 s[8:9], s[8:9], 1
	v_lshl_or_b32 v7, v13, 16, v7
	s_waitcnt lgkmcnt(1)
	v_and_b32_e32 v8, 0xffff, v14
	s_waitcnt lgkmcnt(0)
	v_and_b32_e32 v9, 0xffff, v16
	v_and_or_b32 v11, v13, s91, v11
	v_lshrrev_b32_e32 v12, 16, v14
	v_lshrrev_b32_e32 v13, 16, v16
	v_lshl_add_u64 v[2:3], v[22:23], 0, s[8:9]
	v_lshl_add_u64 v[4:5], v[24:25], 0, s[8:9]
	v_lshl_or_b32 v8, v15, 16, v8
	v_lshl_or_b32 v9, v17, 16, v9
	v_and_or_b32 v12, v15, s91, v12
	v_and_or_b32 v13, v17, s91, v13
	global_store_dwordx4 v[2:3], v[6:9], off
	global_store_dwordx4 v[4:5], v[10:13], off
	ds_read2st64_b32 v[14:15], v35 offset0:64 offset1:72
	ds_read2st64_b32 v[12:13], v35 offset0:80 offset1:88
	ds_read2st64_b32 v[16:17], v35 offset0:96 offset1:104
	ds_read2st64_b32 v[28:29], v35 offset0:112 offset1:120
	s_add_i32 s7, s7, s78
	s_add_i32 s2, s2, s35
	s_waitcnt lgkmcnt(2)
	v_and_b32_e32 v7, 0xffff, v12
	v_lshrrev_b32_e32 v11, 16, v12
	v_and_b32_e32 v6, 0xffff, v14
	v_lshl_or_b32 v7, v13, 16, v7
	s_waitcnt lgkmcnt(1)
	v_and_b32_e32 v8, 0xffff, v16
	s_waitcnt lgkmcnt(0)
	v_and_b32_e32 v9, 0xffff, v28
	v_lshrrev_b32_e32 v10, 16, v14
	v_and_or_b32 v11, v13, s91, v11
	v_lshrrev_b32_e32 v12, 16, v16
	v_lshrrev_b32_e32 v13, 16, v28
	v_lshl_or_b32 v6, v15, 16, v6
	v_lshl_or_b32 v8, v17, 16, v8
	v_lshl_or_b32 v9, v29, 16, v9
	v_and_or_b32 v10, v15, s91, v10
	v_and_or_b32 v12, v17, s91, v12
	v_and_or_b32 v13, v29, s91, v13
	global_store_dwordx4 v[2:3], v[6:9], off offset:16
	global_store_dwordx4 v[4:5], v[10:13], off offset:16
	ds_read2st64_b32 v[14:15], v35 offset0:128 offset1:136
	ds_read2st64_b32 v[12:13], v35 offset0:144 offset1:152
	ds_read2st64_b32 v[16:17], v35 offset0:160 offset1:168
	ds_read2st64_b32 v[28:29], v35 offset0:176 offset1:184
	s_cmpk_gt_i32 s7, 0xbf
	s_waitcnt lgkmcnt(2)
	v_and_b32_e32 v7, 0xffff, v12
	v_lshrrev_b32_e32 v11, 16, v12
	v_and_b32_e32 v6, 0xffff, v14
	v_lshl_or_b32 v7, v13, 16, v7
	s_waitcnt lgkmcnt(1)
	v_and_b32_e32 v8, 0xffff, v16
	s_waitcnt lgkmcnt(0)
	v_and_b32_e32 v9, 0xffff, v28
	v_lshrrev_b32_e32 v10, 16, v14
	v_and_or_b32 v11, v13, s91, v11
	v_lshrrev_b32_e32 v12, 16, v16
	v_lshrrev_b32_e32 v13, 16, v28
	v_lshl_or_b32 v6, v15, 16, v6
	v_lshl_or_b32 v8, v17, 16, v8
	v_lshl_or_b32 v9, v29, 16, v9
	v_and_or_b32 v10, v15, s91, v10
	v_and_or_b32 v12, v17, s91, v12
	v_and_or_b32 v13, v29, s91, v13
	global_store_dwordx4 v[2:3], v[6:9], off offset:32
	global_store_dwordx4 v[4:5], v[10:13], off offset:32
	ds_read2st64_b32 v[14:15], v35 offset0:192 offset1:200
	ds_read2st64_b32 v[12:13], v35 offset0:208 offset1:216
	ds_read2st64_b32 v[16:17], v35 offset0:224 offset1:232
	ds_read2st64_b32 v[28:29], v35 offset0:240 offset1:248
	s_waitcnt lgkmcnt(2)
	v_and_b32_e32 v7, 0xffff, v12
	v_and_b32_e32 v6, 0xffff, v14
	s_waitcnt lgkmcnt(1)
	v_and_b32_e32 v8, 0xffff, v16
	s_waitcnt lgkmcnt(0)
	v_and_b32_e32 v9, 0xffff, v28
	v_lshrrev_b32_e32 v11, 16, v12
	v_lshl_or_b32 v6, v15, 16, v6
	v_lshl_or_b32 v7, v13, 16, v7
	v_lshl_or_b32 v8, v17, 16, v8
	v_lshl_or_b32 v9, v29, 16, v9
	v_lshrrev_b32_e32 v10, 16, v14
	v_and_or_b32 v11, v13, s91, v11
	v_lshrrev_b32_e32 v12, 16, v16
	v_lshrrev_b32_e32 v13, 16, v28
	v_and_or_b32 v10, v15, s91, v10
	v_and_or_b32 v12, v17, s91, v12
	v_and_or_b32 v13, v29, s91, v13
	global_store_dwordx4 v[2:3], v[6:9], off offset:48
	global_store_dwordx4 v[4:5], v[10:13], off offset:48
	ds_read_b32 v10, v36
	ds_read_b32 v11, v37
	ds_read_b32 v12, v38
	ds_read_b32 v13, v39
	ds_read_b32 v14, v40
	ds_read_b32 v15, v41
	ds_read_b32 v16, v42
	ds_read_b32 v17, v43
	s_waitcnt lgkmcnt(7)
	v_and_b32_e32 v6, 0xffff, v10
	v_lshrrev_b32_e32 v10, 16, v10
	s_waitcnt lgkmcnt(6)
	v_lshl_or_b32 v6, v11, 16, v6
	s_waitcnt lgkmcnt(5)
	v_and_b32_e32 v7, 0xffff, v12
	s_waitcnt lgkmcnt(3)
	v_and_b32_e32 v8, 0xffff, v14
	s_waitcnt lgkmcnt(1)
	v_and_b32_e32 v9, 0xffff, v16
	v_and_or_b32 v10, v11, s91, v10
	v_lshrrev_b32_e32 v11, 16, v12
	v_lshl_or_b32 v7, v13, 16, v7
	v_lshl_or_b32 v8, v15, 16, v8
	s_waitcnt lgkmcnt(0)
	v_lshl_or_b32 v9, v17, 16, v9
	v_and_or_b32 v11, v13, s91, v11
	v_lshrrev_b32_e32 v12, 16, v14
	v_lshrrev_b32_e32 v13, 16, v16
	v_and_or_b32 v12, v15, s91, v12
	v_and_or_b32 v13, v17, s91, v13
	global_store_dwordx4 v[2:3], v[6:9], off offset:64
	global_store_dwordx4 v[4:5], v[10:13], off offset:64
	ds_read_b32 v10, v44
	ds_read_b32 v11, v45
	ds_read_b32 v12, v46
	ds_read_b32 v13, v47
	ds_read_b32 v14, v48
	ds_read_b32 v15, v49
	ds_read_b32 v16, v50
	ds_read_b32 v17, v51
	s_waitcnt lgkmcnt(7)
	v_and_b32_e32 v6, 0xffff, v10
	v_lshrrev_b32_e32 v10, 16, v10
	s_waitcnt lgkmcnt(6)
	v_lshl_or_b32 v6, v11, 16, v6
	s_waitcnt lgkmcnt(5)
	v_and_b32_e32 v7, 0xffff, v12
	s_waitcnt lgkmcnt(3)
	v_and_b32_e32 v8, 0xffff, v14
	s_waitcnt lgkmcnt(1)
	v_and_b32_e32 v9, 0xffff, v16
	v_and_or_b32 v10, v11, s91, v10
	v_lshrrev_b32_e32 v11, 16, v12
	v_lshl_or_b32 v7, v13, 16, v7
	v_lshl_or_b32 v8, v15, 16, v8
	s_waitcnt lgkmcnt(0)
	v_lshl_or_b32 v9, v17, 16, v9
	v_and_or_b32 v11, v13, s91, v11
	v_lshrrev_b32_e32 v12, 16, v14
	v_lshrrev_b32_e32 v13, 16, v16
	v_and_or_b32 v12, v15, s91, v12
	v_and_or_b32 v13, v17, s91, v13
	global_store_dwordx4 v[2:3], v[6:9], off offset:80
	global_store_dwordx4 v[4:5], v[10:13], off offset:80
	ds_read_b32 v10, v52
	ds_read_b32 v11, v53
	ds_read_b32 v12, v54
	ds_read_b32 v13, v55
	ds_read_b32 v14, v56
	ds_read_b32 v15, v57
	ds_read_b32 v16, v58
	ds_read_b32 v17, v59
	s_waitcnt lgkmcnt(7)
	v_and_b32_e32 v6, 0xffff, v10
	v_lshrrev_b32_e32 v10, 16, v10
	s_waitcnt lgkmcnt(6)
	v_lshl_or_b32 v6, v11, 16, v6
	s_waitcnt lgkmcnt(5)
	v_and_b32_e32 v7, 0xffff, v12
	s_waitcnt lgkmcnt(3)
	v_and_b32_e32 v8, 0xffff, v14
	s_waitcnt lgkmcnt(1)
	v_and_b32_e32 v9, 0xffff, v16
	v_and_or_b32 v10, v11, s91, v10
	v_lshrrev_b32_e32 v11, 16, v12
	v_lshl_or_b32 v7, v13, 16, v7
	v_lshl_or_b32 v8, v15, 16, v8
	s_waitcnt lgkmcnt(0)
	v_lshl_or_b32 v9, v17, 16, v9
	v_and_or_b32 v11, v13, s91, v11
	v_lshrrev_b32_e32 v12, 16, v14
	v_lshrrev_b32_e32 v13, 16, v16
	v_and_or_b32 v12, v15, s91, v12
	v_and_or_b32 v13, v17, s91, v13
	global_store_dwordx4 v[2:3], v[6:9], off offset:96
	global_store_dwordx4 v[4:5], v[10:13], off offset:96
	ds_read_b32 v10, v60
	ds_read_b32 v11, v61
	ds_read_b32 v12, v62
	ds_read_b32 v13, v63
	ds_read_b32 v14, v64
	ds_read_b32 v15, v65
	ds_read_b32 v16, v66
	ds_read_b32 v17, v67
	s_waitcnt lgkmcnt(7)
	v_and_b32_e32 v6, 0xffff, v10
	v_lshrrev_b32_e32 v10, 16, v10
	s_waitcnt lgkmcnt(6)
	v_lshl_or_b32 v6, v11, 16, v6
	s_waitcnt lgkmcnt(5)
	v_and_b32_e32 v7, 0xffff, v12
	s_waitcnt lgkmcnt(3)
	v_and_b32_e32 v8, 0xffff, v14
	s_waitcnt lgkmcnt(1)
	v_and_b32_e32 v9, 0xffff, v16
	v_and_or_b32 v10, v11, s91, v10
	v_lshrrev_b32_e32 v11, 16, v12
	v_lshl_or_b32 v7, v13, 16, v7
	v_lshl_or_b32 v8, v15, 16, v8
	s_waitcnt lgkmcnt(0)
	v_lshl_or_b32 v9, v17, 16, v9
	v_and_or_b32 v11, v13, s91, v11
	v_lshrrev_b32_e32 v12, 16, v14
	v_lshrrev_b32_e32 v13, 16, v16
	v_and_or_b32 v12, v15, s91, v12
	v_and_or_b32 v13, v17, s91, v13
	global_store_dwordx4 v[2:3], v[6:9], off offset:112
	global_store_dwordx4 v[4:5], v[10:13], off offset:112
	s_barrier
	s_cbranch_scc0 .LBB0_896

PROG:
	.byte	0, 0, 1
	.byte	1, 0, 1
	.byte	3, 0, 1
	.byte	4, 0, 1
	.byte	1, 1, 1
	.byte	5, 0, 1
	.byte	6, 0, 1
	.byte	7, 0, 1
	.byte	8, 0, 1
	.byte	3, 1, 1
	.byte	4, 1, 1
	.byte	3, 2, 1
	.byte	4, 2, 0
	.byte	2, 5, 1
	.byte	9, 0, 0
	.byte	10, 0, 1
	.byte	11, 0, 1
	.byte	8, 1, 1
	.byte	3, 3, 1
	.byte	4, 3, 1
	.byte	3, 4, 1
	.byte	4, 4, 1
	.byte	12, 0, 1
	.byte	13, 0, 1
	.byte	14, 0, 1
	.byte	8, 2, 1
	.byte	3, 5, 1
	.byte	4, 5, 1
	.byte	3, 6, 1
	.byte	4, 6, 1
	.byte	15, 0, 1
	.byte	16, 0, 1
	.byte	8, 3, 1
	.byte	3, 7, 1
	.byte	4, 7, 0
	.size	PROG, 105

	.protected	BGTAB
	.type	BGTAB,@object
	.globl	BGTAB
	.p2align	4, 0x0
